# speedup vs baseline: 1.0251x; 1.0062x over previous
; __device__ __forceinline__ bf16 f2bf(float f) { return (bf16)(pack2(f, 0.f) & 0xffffu); }
; __device__ __forceinline__ float bf2f(bf16 h) { return __uint_as_float(((unsigned)h) << 16); }
; __device__ __forceinline__ void phase_X(const Params& p, const Grp& g) {
;     ...
;         _Pragma("unroll") for (int ai = 0; ai < 2; ++ai) _Pragma("unroll") for (int m = 0; m < 4; ++m) _Pragma("unroll") for (int n = 0; n < 2; ++n) {
;           const int row = ai * 128 + t.wr * 64 + m * 16 + t.fr, col = t.wc * 32 + n * 16 + t.fq * 4;
;           if (col < 4 * g.nb) {
;             const int sp = pm * 256 + row, bl = col >> 2;
;             f32x4 vv = acc[ai][0][m][n];
;             _Pragma("unroll") for (int j = 0; j < 4; ++j) {
;               const size_t idx = (size_t)(bl * 2048 + sp) * 512 + j * 128 + 64;
;               YF[idx] = f2bf(vv[j] * bf2f(SZF[idx]));
;             }
;           }
.LBB0_597:
	v_lshlrev_b32_e32 v133, 9, v131
	v_lshl_add_u32 v134, v128, 6, v132
	v_lshl_or_b32 v135, v129, 14, v133
	v_add_u32_e32 v136, v135, v134
	v_ashrrev_i32_e32 v137, 31, v136
	v_lshlrev_b64 v[136:137], 10, v[136:137]
	v_or_b32_e32 v138, 0x80, v136
	v_mov_b32_e32 v139, v137
	v_lshl_add_u64 v[140:141], s[8:9], 0, v[138:139]
	global_load_ushort v144, v[140:141], off
	v_lshl_add_u64 v[138:139], s[10:11], 0, v[138:139]
	v_or_b32_e32 v142, 16, v134
	v_mov_b32_e32 v160, v138
	v_mov_b32_e32 v161, v139
	v_or_b32_e32 v138, 0x180, v136
	v_mov_b32_e32 v139, v137
	v_lshl_add_u64 v[140:141], s[8:9], 0, v[138:139]
	global_load_ushort v145, v[140:141], off
	v_lshl_add_u64 v[138:139], s[10:11], 0, v[138:139]
	v_mov_b32_e32 v162, v138
	v_mov_b32_e32 v163, v139
	v_or_b32_e32 v138, 0x280, v136
	v_mov_b32_e32 v139, v137
	v_lshl_add_u64 v[140:141], s[8:9], 0, v[138:139]
	global_load_ushort v146, v[140:141], off
	v_lshl_add_u64 v[138:139], s[10:11], 0, v[138:139]
	v_or_b32_e32 v136, 0x380, v136
	v_mov_b32_e32 v164, v138
	v_mov_b32_e32 v165, v139
	v_lshl_add_u64 v[138:139], s[8:9], 0, v[136:137]
	global_load_ushort v147, v[138:139], off
	v_lshl_add_u64 v[136:137], s[10:11], 0, v[136:137]
	v_mov_b32_e32 v166, v136
	v_mov_b32_e32 v167, v137
	v_or_b32_e32 v133, 0x2000, v135
	v_add_u32_e32 v136, v133, v134
	v_ashrrev_i32_e32 v137, 31, v136
	v_lshlrev_b64 v[136:137], 10, v[136:137]
	v_or_b32_e32 v138, 0x80, v136
	v_mov_b32_e32 v139, v137
	v_lshl_add_u64 v[140:141], s[8:9], 0, v[138:139]
	global_load_ushort v148, v[140:141], off
	v_lshl_add_u64 v[138:139], s[10:11], 0, v[138:139]
	v_mov_b32_e32 v168, v138
	v_mov_b32_e32 v169, v139
	v_or_b32_e32 v138, 0x180, v136
	v_mov_b32_e32 v139, v137
	v_lshl_add_u64 v[140:141], s[8:9], 0, v[138:139]
	global_load_ushort v149, v[140:141], off
	v_lshl_add_u64 v[138:139], s[10:11], 0, v[138:139]
	v_mov_b32_e32 v170, v138
	v_mov_b32_e32 v171, v139
	v_or_b32_e32 v138, 0x280, v136
	v_mov_b32_e32 v139, v137
	v_lshl_add_u64 v[140:141], s[8:9], 0, v[138:139]
	global_load_ushort v150, v[140:141], off
	v_lshl_add_u64 v[138:139], s[10:11], 0, v[138:139]
	v_or_b32_e32 v136, 0x380, v136
	v_mov_b32_e32 v172, v138
	v_mov_b32_e32 v173, v139
	v_lshl_add_u64 v[138:139], s[8:9], 0, v[136:137]
	global_load_ushort v151, v[138:139], off
	v_lshl_add_u64 v[136:137], s[10:11], 0, v[136:137]
	v_mov_b32_e32 v174, v136
	v_mov_b32_e32 v175, v137
	v_add_u32_e32 v136, v135, v142
	v_ashrrev_i32_e32 v137, 31, v136
	v_lshlrev_b64 v[136:137], 10, v[136:137]
	v_or_b32_e32 v138, 0x80, v136
	v_mov_b32_e32 v139, v137
	v_lshl_add_u64 v[140:141], s[8:9], 0, v[138:139]
	global_load_ushort v152, v[140:141], off
	v_lshl_add_u64 v[138:139], s[10:11], 0, v[138:139]
	v_mov_b32_e32 v176, v138
	v_mov_b32_e32 v177, v139
	v_or_b32_e32 v138, 0x180, v136
	v_mov_b32_e32 v139, v137
	v_lshl_add_u64 v[140:141], s[8:9], 0, v[138:139]
	global_load_ushort v153, v[140:141], off
	v_lshl_add_u64 v[138:139], s[10:11], 0, v[138:139]
	v_mov_b32_e32 v178, v138
	v_mov_b32_e32 v179, v139
	v_or_b32_e32 v138, 0x280, v136
	v_mov_b32_e32 v139, v137
	v_lshl_add_u64 v[140:141], s[8:9], 0, v[138:139]
	global_load_ushort v154, v[140:141], off
	v_lshl_add_u64 v[138:139], s[10:11], 0, v[138:139]
	v_or_b32_e32 v136, 0x380, v136
	v_mov_b32_e32 v198, v138
	v_mov_b32_e32 v199, v139
	v_lshl_add_u64 v[138:139], s[8:9], 0, v[136:137]
	global_load_ushort v155, v[138:139], off
	v_lshl_add_u64 v[136:137], s[10:11], 0, v[136:137]
	v_mov_b32_e32 v200, v136
	v_mov_b32_e32 v201, v137
	v_add_u32_e32 v136, v133, v142
	v_ashrrev_i32_e32 v137, 31, v136
	v_lshlrev_b64 v[136:137], 10, v[136:137]
	v_or_b32_e32 v138, 0x80, v136
	v_mov_b32_e32 v139, v137
	v_lshl_add_u64 v[140:141], s[8:9], 0, v[138:139]
	global_load_ushort v156, v[140:141], off
	v_lshl_add_u64 v[138:139], s[10:11], 0, v[138:139]
	v_or_b32_e32 v142, 32, v134
	v_mov_b32_e32 v202, v138
	v_mov_b32_e32 v203, v139
	v_or_b32_e32 v138, 0x180, v136
	v_mov_b32_e32 v139, v137
	v_lshl_add_u64 v[140:141], s[8:9], 0, v[138:139]
	global_load_ushort v157, v[140:141], off
	v_lshl_add_u64 v[138:139], s[10:11], 0, v[138:139]
	v_mov_b32_e32 v204, v138
	v_mov_b32_e32 v205, v139
	v_or_b32_e32 v138, 0x280, v136
	v_mov_b32_e32 v139, v137
	v_lshl_add_u64 v[140:141], s[8:9], 0, v[138:139]
	global_load_ushort v158, v[140:141], off
	v_lshl_add_u64 v[138:139], s[10:11], 0, v[138:139]
	v_or_b32_e32 v136, 0x380, v136
	v_mov_b32_e32 v206, v138
	v_mov_b32_e32 v207, v139
	v_lshl_add_u64 v[138:139], s[8:9], 0, v[136:137]
	global_load_ushort v159, v[138:139], off
	v_lshl_add_u64 v[136:137], s[10:11], 0, v[136:137]
	v_mov_b32_e32 v208, v136
	v_mov_b32_e32 v209, v137
	s_waitcnt vmcnt(0)
; __device__ __forceinline__ bf16 f2bf(float f) { return (bf16)(pack2(f, 0.f) & 0xffffu); }
; __device__ __forceinline__ float bf2f(bf16 h) { return __uint_as_float(((unsigned)h) << 16); }
; __device__ __forceinline__ void phase_X(const Params& p, const Grp& g) {
;     ...
;         _Pragma("unroll") for (int ai = 0; ai < 2; ++ai) _Pragma("unroll") for (int m = 0; m < 4; ++m) _Pragma("unroll") for (int n = 0; n < 2; ++n) {
;           const int row = ai * 128 + t.wr * 64 + m * 16 + t.fr, col = t.wc * 32 + n * 16 + t.fq * 4;
;           if (col < 4 * g.nb) {
;             const int sp = pm * 256 + row, bl = col >> 2;
;             f32x4 vv = acc[ai][0][m][n];
;             _Pragma("unroll") for (int j = 0; j < 4; ++j) {
;               const size_t idx = (size_t)(bl * 2048 + sp) * 512 + j * 128 + 64;
;               YF[idx] = f2bf(vv[j] * bf2f(SZF[idx]));
;             }
;           }
	v_lshlrev_b32_e32 v144, 16, v144
	v_mul_f32_e32 v144, v124, v144
	v_cvt_pk_bf16_f32 v144, v144, s0
	global_store_short v[160:161], v144, off
	v_lshlrev_b32_e32 v145, 16, v145
	v_mul_f32_e32 v145, v125, v145
	v_cvt_pk_bf16_f32 v145, v145, s0
	global_store_short v[162:163], v145, off
	v_lshlrev_b32_e32 v146, 16, v146
	v_mul_f32_e32 v146, v126, v146
	v_cvt_pk_bf16_f32 v146, v146, s0
	global_store_short v[164:165], v146, off
	v_lshlrev_b32_e32 v147, 16, v147
	v_mul_f32_e32 v147, v127, v147
	v_cvt_pk_bf16_f32 v147, v147, s0
	global_store_short v[166:167], v147, off
	v_lshlrev_b32_e32 v148, 16, v148
	v_mul_f32_e32 v148, v120, v148
	v_cvt_pk_bf16_f32 v148, v148, s0
	global_store_short v[168:169], v148, off
	v_lshlrev_b32_e32 v149, 16, v149
	v_mul_f32_e32 v149, v121, v149
	v_cvt_pk_bf16_f32 v149, v149, s0
	global_store_short v[170:171], v149, off
	v_lshlrev_b32_e32 v150, 16, v150
	v_mul_f32_e32 v150, v122, v150
	v_cvt_pk_bf16_f32 v150, v150, s0
	global_store_short v[172:173], v150, off
	v_lshlrev_b32_e32 v151, 16, v151
	v_mul_f32_e32 v151, v123, v151
	v_cvt_pk_bf16_f32 v151, v151, s0
	global_store_short v[174:175], v151, off
	v_lshlrev_b32_e32 v152, 16, v152
	v_mul_f32_e32 v152, v116, v152
	v_cvt_pk_bf16_f32 v152, v152, s0
	global_store_short v[176:177], v152, off
	v_lshlrev_b32_e32 v153, 16, v153
	v_mul_f32_e32 v153, v117, v153
	v_cvt_pk_bf16_f32 v153, v153, s0
	global_store_short v[178:179], v153, off
	v_lshlrev_b32_e32 v154, 16, v154
	v_mul_f32_e32 v154, v118, v154
	v_cvt_pk_bf16_f32 v154, v154, s0
	global_store_short v[198:199], v154, off
	v_lshlrev_b32_e32 v155, 16, v155
	v_mul_f32_e32 v155, v119, v155
	v_cvt_pk_bf16_f32 v155, v155, s0
	global_store_short v[200:201], v155, off
	v_lshlrev_b32_e32 v156, 16, v156
	v_mul_f32_e32 v156, v112, v156
	v_cvt_pk_bf16_f32 v156, v156, s0
	global_store_short v[202:203], v156, off
	v_lshlrev_b32_e32 v157, 16, v157
	v_mul_f32_e32 v157, v113, v157
	v_cvt_pk_bf16_f32 v157, v157, s0
	global_store_short v[204:205], v157, off
	v_lshlrev_b32_e32 v158, 16, v158
	v_mul_f32_e32 v158, v114, v158
	v_cvt_pk_bf16_f32 v158, v158, s0
	global_store_short v[206:207], v158, off
	v_lshlrev_b32_e32 v159, 16, v159
	v_mul_f32_e32 v159, v115, v159
	v_cvt_pk_bf16_f32 v159, v159, s0
	global_store_short v[208:209], v159, off
	v_add_u32_e32 v136, v135, v142
	v_ashrrev_i32_e32 v137, 31, v136
	v_lshlrev_b64 v[136:137], 10, v[136:137]
	v_or_b32_e32 v138, 0x80, v136
	v_mov_b32_e32 v139, v137
	v_lshl_add_u64 v[140:141], s[8:9], 0, v[138:139]
	global_load_ushort v144, v[140:141], off
	v_lshl_add_u64 v[138:139], s[10:11], 0, v[138:139]
	v_mov_b32_e32 v160, v138
	v_mov_b32_e32 v161, v139
	v_or_b32_e32 v138, 0x180, v136
	v_mov_b32_e32 v139, v137
	v_lshl_add_u64 v[140:141], s[8:9], 0, v[138:139]
	global_load_ushort v145, v[140:141], off
	v_lshl_add_u64 v[138:139], s[10:11], 0, v[138:139]
	v_mov_b32_e32 v162, v138
	v_mov_b32_e32 v163, v139
	v_or_b32_e32 v138, 0x280, v136
	v_mov_b32_e32 v139, v137
	v_lshl_add_u64 v[140:141], s[8:9], 0, v[138:139]
	global_load_ushort v146, v[140:141], off
	v_lshl_add_u64 v[138:139], s[10:11], 0, v[138:139]
	v_or_b32_e32 v136, 0x380, v136
	v_mov_b32_e32 v164, v138
	v_mov_b32_e32 v165, v139
	v_lshl_add_u64 v[138:139], s[8:9], 0, v[136:137]
	global_load_ushort v147, v[138:139], off
	v_lshl_add_u64 v[136:137], s[10:11], 0, v[136:137]
	v_mov_b32_e32 v166, v136
	v_mov_b32_e32 v167, v137
	v_add_u32_e32 v136, v133, v142
	v_ashrrev_i32_e32 v137, 31, v136
	v_lshlrev_b64 v[136:137], 10, v[136:137]
	v_or_b32_e32 v138, 0x80, v136
	v_mov_b32_e32 v139, v137
	v_lshl_add_u64 v[140:141], s[8:9], 0, v[138:139]
	global_load_ushort v148, v[140:141], off
	v_lshl_add_u64 v[138:139], s[10:11], 0, v[138:139]
	v_or_b32_e32 v142, 48, v134
	v_mov_b32_e32 v168, v138
	v_mov_b32_e32 v169, v139
	v_or_b32_e32 v138, 0x180, v136
	v_mov_b32_e32 v139, v137
	v_lshl_add_u64 v[140:141], s[8:9], 0, v[138:139]
	global_load_ushort v149, v[140:141], off
	v_lshl_add_u64 v[138:139], s[10:11], 0, v[138:139]
	v_mov_b32_e32 v170, v138
	v_mov_b32_e32 v171, v139
	v_or_b32_e32 v138, 0x280, v136
	v_mov_b32_e32 v139, v137
	v_lshl_add_u64 v[140:141], s[8:9], 0, v[138:139]
	global_load_ushort v150, v[140:141], off
	v_lshl_add_u64 v[138:139], s[10:11], 0, v[138:139]
	v_or_b32_e32 v136, 0x380, v136
	v_mov_b32_e32 v172, v138
	v_mov_b32_e32 v173, v139
	v_lshl_add_u64 v[138:139], s[8:9], 0, v[136:137]
	global_load_ushort v151, v[138:139], off
	v_lshl_add_u64 v[136:137], s[10:11], 0, v[136:137]
	v_mov_b32_e32 v174, v136
	v_mov_b32_e32 v175, v137
	v_add_u32_e32 v136, v135, v142
	v_ashrrev_i32_e32 v137, 31, v136
	v_lshlrev_b64 v[136:137], 10, v[136:137]
	v_or_b32_e32 v138, 0x80, v136
	v_mov_b32_e32 v139, v137
	v_lshl_add_u64 v[140:141], s[8:9], 0, v[138:139]
	global_load_ushort v152, v[140:141], off
	v_lshl_add_u64 v[138:139], s[10:11], 0, v[138:139]
	v_mov_b32_e32 v176, v138
	v_mov_b32_e32 v177, v139
	v_or_b32_e32 v138, 0x180, v136
	v_mov_b32_e32 v139, v137
	v_lshl_add_u64 v[140:141], s[8:9], 0, v[138:139]
	global_load_ushort v153, v[140:141], off
	v_lshl_add_u64 v[138:139], s[10:11], 0, v[138:139]
	v_mov_b32_e32 v178, v138
	v_mov_b32_e32 v179, v139
	v_or_b32_e32 v138, 0x280, v136
	v_mov_b32_e32 v139, v137
	v_lshl_add_u64 v[140:141], s[8:9], 0, v[138:139]
	global_load_ushort v154, v[140:141], off
	v_lshl_add_u64 v[138:139], s[10:11], 0, v[138:139]
	v_or_b32_e32 v136, 0x380, v136
	v_mov_b32_e32 v198, v138
	v_mov_b32_e32 v199, v139
	v_lshl_add_u64 v[138:139], s[8:9], 0, v[136:137]
	global_load_ushort v155, v[138:139], off
	v_lshl_add_u64 v[136:137], s[10:11], 0, v[136:137]
	v_mov_b32_e32 v200, v136
	v_mov_b32_e32 v201, v137
	v_add_u32_e32 v136, v133, v142
	v_ashrrev_i32_e32 v137, 31, v136
	v_lshlrev_b64 v[136:137], 10, v[136:137]
	v_or_b32_e32 v138, 0x80, v136
	v_mov_b32_e32 v139, v137
	v_lshl_add_u64 v[140:141], s[8:9], 0, v[138:139]
	global_load_ushort v156, v[140:141], off
	v_lshl_add_u64 v[138:139], s[10:11], 0, v[138:139]
	v_add_u32_e32 v142, 0x80, v134
	v_mov_b32_e32 v202, v138
	v_mov_b32_e32 v203, v139
	v_or_b32_e32 v138, 0x180, v136
	v_mov_b32_e32 v139, v137
	v_lshl_add_u64 v[140:141], s[8:9], 0, v[138:139]
	global_load_ushort v157, v[140:141], off
	v_lshl_add_u64 v[138:139], s[10:11], 0, v[138:139]
	v_mov_b32_e32 v204, v138
	v_mov_b32_e32 v205, v139
	v_or_b32_e32 v138, 0x280, v136
	v_mov_b32_e32 v139, v137
	v_lshl_add_u64 v[140:141], s[8:9], 0, v[138:139]
	global_load_ushort v158, v[140:141], off
	v_lshl_add_u64 v[138:139], s[10:11], 0, v[138:139]
	v_or_b32_e32 v136, 0x380, v136
	v_mov_b32_e32 v206, v138
	v_mov_b32_e32 v207, v139
	v_lshl_add_u64 v[138:139], s[8:9], 0, v[136:137]
	global_load_ushort v159, v[138:139], off
	v_lshl_add_u64 v[136:137], s[10:11], 0, v[136:137]
	v_mov_b32_e32 v208, v136
	v_mov_b32_e32 v209, v137
	s_waitcnt vmcnt(0)
; __device__ __forceinline__ bf16 f2bf(float f) { return (bf16)(pack2(f, 0.f) & 0xffffu); }
; __device__ __forceinline__ float bf2f(bf16 h) { return __uint_as_float(((unsigned)h) << 16); }
; __device__ __forceinline__ void phase_X(const Params& p, const Grp& g) {
;     ...
;         _Pragma("unroll") for (int ai = 0; ai < 2; ++ai) _Pragma("unroll") for (int m = 0; m < 4; ++m) _Pragma("unroll") for (int n = 0; n < 2; ++n) {
;           const int row = ai * 128 + t.wr * 64 + m * 16 + t.fr, col = t.wc * 32 + n * 16 + t.fq * 4;
;           if (col < 4 * g.nb) {
;             const int sp = pm * 256 + row, bl = col >> 2;
;             f32x4 vv = acc[ai][0][m][n];
;             _Pragma("unroll") for (int j = 0; j < 4; ++j) {
;               const size_t idx = (size_t)(bl * 2048 + sp) * 512 + j * 128 + 64;
;               YF[idx] = f2bf(vv[j] * bf2f(SZF[idx]));
;             }
;           }
	v_lshlrev_b32_e32 v144, 16, v144
	v_mul_f32_e32 v144, v108, v144
	v_cvt_pk_bf16_f32 v144, v144, s0
	global_store_short v[160:161], v144, off
	v_lshlrev_b32_e32 v145, 16, v145
	v_mul_f32_e32 v145, v109, v145
	v_cvt_pk_bf16_f32 v145, v145, s0
	global_store_short v[162:163], v145, off
	v_lshlrev_b32_e32 v146, 16, v146
	v_mul_f32_e32 v146, v110, v146
	v_cvt_pk_bf16_f32 v146, v146, s0
	global_store_short v[164:165], v146, off
	v_lshlrev_b32_e32 v147, 16, v147
	v_mul_f32_e32 v147, v111, v147
	v_cvt_pk_bf16_f32 v147, v147, s0
	global_store_short v[166:167], v147, off
	v_lshlrev_b32_e32 v148, 16, v148
	v_mul_f32_e32 v148, v104, v148
	v_cvt_pk_bf16_f32 v148, v148, s0
	global_store_short v[168:169], v148, off
	v_lshlrev_b32_e32 v149, 16, v149
	v_mul_f32_e32 v149, v105, v149
	v_cvt_pk_bf16_f32 v149, v149, s0
	global_store_short v[170:171], v149, off
	v_lshlrev_b32_e32 v150, 16, v150
	v_mul_f32_e32 v150, v106, v150
	v_cvt_pk_bf16_f32 v150, v150, s0
	global_store_short v[172:173], v150, off
	v_lshlrev_b32_e32 v151, 16, v151
	v_mul_f32_e32 v151, v107, v151
	v_cvt_pk_bf16_f32 v151, v151, s0
	global_store_short v[174:175], v151, off
	v_lshlrev_b32_e32 v152, 16, v152
	v_mul_f32_e32 v152, v100, v152
	v_cvt_pk_bf16_f32 v152, v152, s0
	global_store_short v[176:177], v152, off
	v_lshlrev_b32_e32 v153, 16, v153
	v_mul_f32_e32 v153, v101, v153
	v_cvt_pk_bf16_f32 v153, v153, s0
	global_store_short v[178:179], v153, off
	v_lshlrev_b32_e32 v154, 16, v154
	v_mul_f32_e32 v154, v102, v154
	v_cvt_pk_bf16_f32 v154, v154, s0
	global_store_short v[198:199], v154, off
	v_lshlrev_b32_e32 v155, 16, v155
	v_mul_f32_e32 v155, v103, v155
	v_cvt_pk_bf16_f32 v155, v155, s0
	global_store_short v[200:201], v155, off
	v_lshlrev_b32_e32 v156, 16, v156
	v_mul_f32_e32 v156, v96, v156
	v_cvt_pk_bf16_f32 v156, v156, s0
	global_store_short v[202:203], v156, off
	v_lshlrev_b32_e32 v157, 16, v157
	v_mul_f32_e32 v157, v97, v157
	v_cvt_pk_bf16_f32 v157, v157, s0
	global_store_short v[204:205], v157, off
	v_lshlrev_b32_e32 v158, 16, v158
	v_mul_f32_e32 v158, v98, v158
	v_cvt_pk_bf16_f32 v158, v158, s0
	global_store_short v[206:207], v158, off
	v_lshlrev_b32_e32 v159, 16, v159
	v_mul_f32_e32 v159, v99, v159
	v_cvt_pk_bf16_f32 v159, v159, s0
	global_store_short v[208:209], v159, off
	v_add_u32_e32 v136, v135, v142
	v_ashrrev_i32_e32 v137, 31, v136
	v_lshlrev_b64 v[136:137], 10, v[136:137]
	v_or_b32_e32 v138, 0x80, v136
	v_mov_b32_e32 v139, v137
	v_lshl_add_u64 v[140:141], s[8:9], 0, v[138:139]
	global_load_ushort v144, v[140:141], off
	v_lshl_add_u64 v[138:139], s[10:11], 0, v[138:139]
	v_mov_b32_e32 v160, v138
	v_mov_b32_e32 v161, v139
	v_or_b32_e32 v138, 0x180, v136
	v_mov_b32_e32 v139, v137
	v_lshl_add_u64 v[140:141], s[8:9], 0, v[138:139]
	global_load_ushort v145, v[140:141], off
	v_lshl_add_u64 v[138:139], s[10:11], 0, v[138:139]
	v_mov_b32_e32 v162, v138
	v_mov_b32_e32 v163, v139
	v_or_b32_e32 v138, 0x280, v136
	v_mov_b32_e32 v139, v137
	v_lshl_add_u64 v[140:141], s[8:9], 0, v[138:139]
	global_load_ushort v146, v[140:141], off
	v_lshl_add_u64 v[138:139], s[10:11], 0, v[138:139]
	v_or_b32_e32 v136, 0x380, v136
	v_mov_b32_e32 v164, v138
	v_mov_b32_e32 v165, v139
	v_lshl_add_u64 v[138:139], s[8:9], 0, v[136:137]
	global_load_ushort v147, v[138:139], off
	v_lshl_add_u64 v[136:137], s[10:11], 0, v[136:137]
	v_mov_b32_e32 v166, v136
	v_mov_b32_e32 v167, v137
	v_add_u32_e32 v136, v133, v142
	v_ashrrev_i32_e32 v137, 31, v136
	v_lshlrev_b64 v[136:137], 10, v[136:137]
	v_or_b32_e32 v138, 0x80, v136
	v_mov_b32_e32 v139, v137
	v_lshl_add_u64 v[140:141], s[8:9], 0, v[138:139]
	global_load_ushort v148, v[140:141], off
	v_lshl_add_u64 v[138:139], s[10:11], 0, v[138:139]
	v_add_u32_e32 v142, 0x90, v134
	v_mov_b32_e32 v168, v138
	v_mov_b32_e32 v169, v139
	v_or_b32_e32 v138, 0x180, v136
	v_mov_b32_e32 v139, v137
	v_lshl_add_u64 v[140:141], s[8:9], 0, v[138:139]
	global_load_ushort v149, v[140:141], off
	v_lshl_add_u64 v[138:139], s[10:11], 0, v[138:139]
	v_mov_b32_e32 v170, v138
	v_mov_b32_e32 v171, v139
	v_or_b32_e32 v138, 0x280, v136
	v_mov_b32_e32 v139, v137
	v_lshl_add_u64 v[140:141], s[8:9], 0, v[138:139]
	global_load_ushort v150, v[140:141], off
	v_lshl_add_u64 v[138:139], s[10:11], 0, v[138:139]
	v_or_b32_e32 v136, 0x380, v136
	v_mov_b32_e32 v172, v138
	v_mov_b32_e32 v173, v139
	v_lshl_add_u64 v[138:139], s[8:9], 0, v[136:137]
	global_load_ushort v151, v[138:139], off
	v_lshl_add_u64 v[136:137], s[10:11], 0, v[136:137]
	v_mov_b32_e32 v174, v136
	v_mov_b32_e32 v175, v137
	v_add_u32_e32 v136, v135, v142
	v_ashrrev_i32_e32 v137, 31, v136
	v_lshlrev_b64 v[136:137], 10, v[136:137]
	v_or_b32_e32 v138, 0x80, v136
	v_mov_b32_e32 v139, v137
	v_lshl_add_u64 v[140:141], s[8:9], 0, v[138:139]
	global_load_ushort v152, v[140:141], off
	v_lshl_add_u64 v[138:139], s[10:11], 0, v[138:139]
	v_mov_b32_e32 v176, v138
	v_mov_b32_e32 v177, v139
	v_or_b32_e32 v138, 0x180, v136
	v_mov_b32_e32 v139, v137
	v_lshl_add_u64 v[140:141], s[8:9], 0, v[138:139]
	global_load_ushort v153, v[140:141], off
	v_lshl_add_u64 v[138:139], s[10:11], 0, v[138:139]
	v_mov_b32_e32 v178, v138
	v_mov_b32_e32 v179, v139
	v_or_b32_e32 v138, 0x280, v136
	v_mov_b32_e32 v139, v137
	v_lshl_add_u64 v[140:141], s[8:9], 0, v[138:139]
	global_load_ushort v154, v[140:141], off
	v_lshl_add_u64 v[138:139], s[10:11], 0, v[138:139]
	v_or_b32_e32 v136, 0x380, v136
	v_mov_b32_e32 v198, v138
	v_mov_b32_e32 v199, v139
	v_lshl_add_u64 v[138:139], s[8:9], 0, v[136:137]
	global_load_ushort v155, v[138:139], off
	v_lshl_add_u64 v[136:137], s[10:11], 0, v[136:137]
	v_mov_b32_e32 v200, v136
	v_mov_b32_e32 v201, v137
	v_add_u32_e32 v136, v133, v142
	v_ashrrev_i32_e32 v137, 31, v136
	v_lshlrev_b64 v[136:137], 10, v[136:137]
	v_or_b32_e32 v138, 0x80, v136
	v_mov_b32_e32 v139, v137
	v_lshl_add_u64 v[140:141], s[8:9], 0, v[138:139]
	global_load_ushort v156, v[140:141], off
	v_lshl_add_u64 v[138:139], s[10:11], 0, v[138:139]
	v_add_u32_e32 v142, 0xa0, v134
	v_mov_b32_e32 v202, v138
	v_mov_b32_e32 v203, v139
	v_or_b32_e32 v138, 0x180, v136
	v_mov_b32_e32 v139, v137
	v_lshl_add_u64 v[140:141], s[8:9], 0, v[138:139]
	global_load_ushort v157, v[140:141], off
	v_lshl_add_u64 v[138:139], s[10:11], 0, v[138:139]
	v_mov_b32_e32 v204, v138
	v_mov_b32_e32 v205, v139
	v_or_b32_e32 v138, 0x280, v136
	v_mov_b32_e32 v139, v137
	v_lshl_add_u64 v[140:141], s[8:9], 0, v[138:139]
	global_load_ushort v158, v[140:141], off
	v_lshl_add_u64 v[138:139], s[10:11], 0, v[138:139]
	v_or_b32_e32 v136, 0x380, v136
	v_mov_b32_e32 v206, v138
	v_mov_b32_e32 v207, v139
	v_lshl_add_u64 v[138:139], s[8:9], 0, v[136:137]
	global_load_ushort v159, v[138:139], off
	v_lshl_add_u64 v[136:137], s[10:11], 0, v[136:137]
	v_mov_b32_e32 v208, v136
	v_mov_b32_e32 v209, v137
	s_waitcnt vmcnt(0)
; __device__ __forceinline__ bf16 f2bf(float f) { return (bf16)(pack2(f, 0.f) & 0xffffu); }
; __device__ __forceinline__ float bf2f(bf16 h) { return __uint_as_float(((unsigned)h) << 16); }
; __device__ __forceinline__ void phase_X(const Params& p, const Grp& g) {
;     ...
;         _Pragma("unroll") for (int ai = 0; ai < 2; ++ai) _Pragma("unroll") for (int m = 0; m < 4; ++m) _Pragma("unroll") for (int n = 0; n < 2; ++n) {
;           const int row = ai * 128 + t.wr * 64 + m * 16 + t.fr, col = t.wc * 32 + n * 16 + t.fq * 4;
;           if (col < 4 * g.nb) {
;             const int sp = pm * 256 + row, bl = col >> 2;
;             f32x4 vv = acc[ai][0][m][n];
;             _Pragma("unroll") for (int j = 0; j < 4; ++j) {
;               const size_t idx = (size_t)(bl * 2048 + sp) * 512 + j * 128 + 64;
;               YF[idx] = f2bf(vv[j] * bf2f(SZF[idx]));
;             }
;           }
	v_lshlrev_b32_e32 v144, 16, v144
	v_mul_f32_e32 v144, v60, v144
	v_cvt_pk_bf16_f32 v144, v144, s0
	global_store_short v[160:161], v144, off
	v_lshlrev_b32_e32 v145, 16, v145
	v_mul_f32_e32 v145, v61, v145
	v_cvt_pk_bf16_f32 v145, v145, s0
	global_store_short v[162:163], v145, off
	v_lshlrev_b32_e32 v146, 16, v146
	v_mul_f32_e32 v146, v62, v146
	v_cvt_pk_bf16_f32 v146, v146, s0
	global_store_short v[164:165], v146, off
	v_lshlrev_b32_e32 v147, 16, v147
	v_mul_f32_e32 v147, v63, v147
	v_cvt_pk_bf16_f32 v147, v147, s0
	global_store_short v[166:167], v147, off
	v_lshlrev_b32_e32 v148, 16, v148
	v_mul_f32_e32 v148, v56, v148
	v_cvt_pk_bf16_f32 v148, v148, s0
	global_store_short v[168:169], v148, off
	v_lshlrev_b32_e32 v149, 16, v149
	v_mul_f32_e32 v149, v57, v149
	v_cvt_pk_bf16_f32 v149, v149, s0
	global_store_short v[170:171], v149, off
	v_lshlrev_b32_e32 v150, 16, v150
	v_mul_f32_e32 v150, v58, v150
	v_cvt_pk_bf16_f32 v150, v150, s0
	global_store_short v[172:173], v150, off
	v_lshlrev_b32_e32 v151, 16, v151
	v_mul_f32_e32 v151, v59, v151
	v_cvt_pk_bf16_f32 v151, v151, s0
	global_store_short v[174:175], v151, off
	v_lshlrev_b32_e32 v152, 16, v152
	v_mul_f32_e32 v152, v52, v152
	v_cvt_pk_bf16_f32 v152, v152, s0
	global_store_short v[176:177], v152, off
	v_lshlrev_b32_e32 v153, 16, v153
	v_mul_f32_e32 v153, v53, v153
	v_cvt_pk_bf16_f32 v153, v153, s0
	global_store_short v[178:179], v153, off
	v_lshlrev_b32_e32 v154, 16, v154
	v_mul_f32_e32 v154, v54, v154
	v_cvt_pk_bf16_f32 v154, v154, s0
	global_store_short v[198:199], v154, off
	v_lshlrev_b32_e32 v155, 16, v155
	v_mul_f32_e32 v155, v55, v155
	v_cvt_pk_bf16_f32 v155, v155, s0
	global_store_short v[200:201], v155, off
	v_lshlrev_b32_e32 v156, 16, v156
	v_mul_f32_e32 v156, v48, v156
	v_cvt_pk_bf16_f32 v156, v156, s0
	global_store_short v[202:203], v156, off
	v_lshlrev_b32_e32 v157, 16, v157
	v_mul_f32_e32 v157, v49, v157
	v_cvt_pk_bf16_f32 v157, v157, s0
	global_store_short v[204:205], v157, off
	v_lshlrev_b32_e32 v158, 16, v158
	v_mul_f32_e32 v158, v50, v158
	v_cvt_pk_bf16_f32 v158, v158, s0
	global_store_short v[206:207], v158, off
	v_lshlrev_b32_e32 v159, 16, v159
	v_mul_f32_e32 v159, v51, v159
	v_cvt_pk_bf16_f32 v159, v159, s0
	global_store_short v[208:209], v159, off
	v_add_u32_e32 v136, v135, v142
	v_ashrrev_i32_e32 v137, 31, v136
	v_lshlrev_b64 v[136:137], 10, v[136:137]
	v_or_b32_e32 v138, 0x80, v136
	v_mov_b32_e32 v139, v137
	v_lshl_add_u64 v[140:141], s[8:9], 0, v[138:139]
	global_load_ushort v144, v[140:141], off
	v_lshl_add_u64 v[138:139], s[10:11], 0, v[138:139]
	v_mov_b32_e32 v160, v138
	v_mov_b32_e32 v161, v139
	v_or_b32_e32 v138, 0x180, v136
	v_mov_b32_e32 v139, v137
	v_lshl_add_u64 v[140:141], s[8:9], 0, v[138:139]
	global_load_ushort v145, v[140:141], off
	v_lshl_add_u64 v[138:139], s[10:11], 0, v[138:139]
	v_mov_b32_e32 v162, v138
	v_mov_b32_e32 v163, v139
	v_or_b32_e32 v138, 0x280, v136
	v_mov_b32_e32 v139, v137
	v_lshl_add_u64 v[140:141], s[8:9], 0, v[138:139]
	global_load_ushort v146, v[140:141], off
	v_lshl_add_u64 v[138:139], s[10:11], 0, v[138:139]
	v_or_b32_e32 v136, 0x380, v136
	v_mov_b32_e32 v164, v138
	v_mov_b32_e32 v165, v139
	v_lshl_add_u64 v[138:139], s[8:9], 0, v[136:137]
	global_load_ushort v147, v[138:139], off
	v_lshl_add_u64 v[136:137], s[10:11], 0, v[136:137]
	v_mov_b32_e32 v166, v136
	v_mov_b32_e32 v167, v137
	v_add_u32_e32 v136, v133, v142
	v_ashrrev_i32_e32 v137, 31, v136
	v_lshlrev_b64 v[136:137], 10, v[136:137]
	v_or_b32_e32 v138, 0x80, v136
	v_mov_b32_e32 v139, v137
	v_lshl_add_u64 v[140:141], s[8:9], 0, v[138:139]
	global_load_ushort v148, v[140:141], off
	v_lshl_add_u64 v[138:139], s[10:11], 0, v[138:139]
	v_mov_b32_e32 v168, v138
	v_mov_b32_e32 v169, v139
	v_or_b32_e32 v138, 0x180, v136
	v_mov_b32_e32 v139, v137
	v_lshl_add_u64 v[140:141], s[8:9], 0, v[138:139]
	global_load_ushort v149, v[140:141], off
	v_lshl_add_u64 v[138:139], s[10:11], 0, v[138:139]
	v_mov_b32_e32 v170, v138
	v_mov_b32_e32 v171, v139
	v_or_b32_e32 v138, 0x280, v136
	v_mov_b32_e32 v139, v137
	v_lshl_add_u64 v[140:141], s[8:9], 0, v[138:139]
	global_load_ushort v150, v[140:141], off
	v_lshl_add_u64 v[138:139], s[10:11], 0, v[138:139]
	v_or_b32_e32 v136, 0x380, v136
	v_mov_b32_e32 v172, v138
	v_mov_b32_e32 v173, v139
	v_lshl_add_u64 v[138:139], s[8:9], 0, v[136:137]
	global_load_ushort v151, v[138:139], off
	v_add_u32_e32 v140, 0xb0, v134
	v_add_u32_e32 v134, v135, v140
	v_ashrrev_i32_e32 v135, 31, v134
	v_lshl_add_u64 v[136:137], s[10:11], 0, v[136:137]
	v_lshlrev_b64 v[134:135], 10, v[134:135]
	v_mov_b32_e32 v174, v136
	v_mov_b32_e32 v175, v137
	v_or_b32_e32 v136, 0x80, v134
	v_mov_b32_e32 v137, v135
	v_lshl_add_u64 v[138:139], s[8:9], 0, v[136:137]
	global_load_ushort v152, v[138:139], off
	v_lshl_add_u64 v[136:137], s[10:11], 0, v[136:137]
	v_mov_b32_e32 v176, v136
	v_mov_b32_e32 v177, v137
	v_or_b32_e32 v136, 0x180, v134
	v_mov_b32_e32 v137, v135
	v_lshl_add_u64 v[138:139], s[8:9], 0, v[136:137]
	global_load_ushort v153, v[138:139], off
	v_lshl_add_u64 v[136:137], s[10:11], 0, v[136:137]
	v_mov_b32_e32 v178, v136
	v_mov_b32_e32 v179, v137
	v_or_b32_e32 v136, 0x280, v134
	v_mov_b32_e32 v137, v135
	v_lshl_add_u64 v[138:139], s[8:9], 0, v[136:137]
	global_load_ushort v154, v[138:139], off
	v_lshl_add_u64 v[136:137], s[10:11], 0, v[136:137]
	v_or_b32_e32 v134, 0x380, v134
	v_mov_b32_e32 v198, v136
	v_mov_b32_e32 v199, v137
	v_lshl_add_u64 v[136:137], s[8:9], 0, v[134:135]
	global_load_ushort v155, v[136:137], off
	v_lshl_add_u64 v[134:135], s[10:11], 0, v[134:135]
	v_mov_b32_e32 v200, v134
	v_mov_b32_e32 v201, v135
	v_add_u32_e32 v134, v133, v140
	v_ashrrev_i32_e32 v135, 31, v134
	v_lshlrev_b64 v[134:135], 10, v[134:135]
	v_or_b32_e32 v136, 0x80, v134
	v_mov_b32_e32 v137, v135
	v_lshl_add_u64 v[138:139], s[8:9], 0, v[136:137]
	global_load_ushort v156, v[138:139], off
	v_lshl_add_u64 v[136:137], s[10:11], 0, v[136:137]
	v_mov_b32_e32 v202, v136
	v_mov_b32_e32 v203, v137
	v_or_b32_e32 v136, 0x180, v134
	v_mov_b32_e32 v137, v135
	v_lshl_add_u64 v[138:139], s[8:9], 0, v[136:137]
	global_load_ushort v157, v[138:139], off
	v_lshl_add_u64 v[136:137], s[10:11], 0, v[136:137]
	v_mov_b32_e32 v204, v136
	v_mov_b32_e32 v205, v137
	v_or_b32_e32 v136, 0x280, v134
	v_mov_b32_e32 v137, v135
	v_lshl_add_u64 v[138:139], s[8:9], 0, v[136:137]
	global_load_ushort v158, v[138:139], off
	v_lshl_add_u64 v[136:137], s[10:11], 0, v[136:137]
	v_or_b32_e32 v134, 0x380, v134
	v_mov_b32_e32 v206, v136
	v_mov_b32_e32 v207, v137
	v_lshl_add_u64 v[136:137], s[8:9], 0, v[134:135]
	global_load_ushort v159, v[136:137], off
	v_lshl_add_u64 v[134:135], s[10:11], 0, v[134:135]
	v_mov_b32_e32 v208, v134
	v_mov_b32_e32 v209, v135
	s_waitcnt vmcnt(0)
; __device__ __forceinline__ bf16 f2bf(float f) { return (bf16)(pack2(f, 0.f) & 0xffffu); }
; __device__ __forceinline__ float bf2f(bf16 h) { return __uint_as_float(((unsigned)h) << 16); }
; __device__ __forceinline__ void phase_X(const Params& p, const Grp& g) {
;     ...
;         _Pragma("unroll") for (int ai = 0; ai < 2; ++ai) _Pragma("unroll") for (int m = 0; m < 4; ++m) _Pragma("unroll") for (int n = 0; n < 2; ++n) {
;           const int row = ai * 128 + t.wr * 64 + m * 16 + t.fr, col = t.wc * 32 + n * 16 + t.fq * 4;
;           if (col < 4 * g.nb) {
;             const int sp = pm * 256 + row, bl = col >> 2;
;             f32x4 vv = acc[ai][0][m][n];
;             _Pragma("unroll") for (int j = 0; j < 4; ++j) {
;               const size_t idx = (size_t)(bl * 2048 + sp) * 512 + j * 128 + 64;
;               YF[idx] = f2bf(vv[j] * bf2f(SZF[idx]));
;             }
;           }
	v_lshlrev_b32_e32 v144, 16, v144
	v_mul_f32_e32 v144, v44, v144
	v_cvt_pk_bf16_f32 v144, v144, s0
	global_store_short v[160:161], v144, off
	v_lshlrev_b32_e32 v145, 16, v145
	v_mul_f32_e32 v145, v45, v145
	v_cvt_pk_bf16_f32 v145, v145, s0
	global_store_short v[162:163], v145, off
	v_lshlrev_b32_e32 v146, 16, v146
	v_mul_f32_e32 v146, v46, v146
	v_cvt_pk_bf16_f32 v146, v146, s0
	global_store_short v[164:165], v146, off
	v_lshlrev_b32_e32 v147, 16, v147
	v_mul_f32_e32 v147, v47, v147
	v_cvt_pk_bf16_f32 v147, v147, s0
	global_store_short v[166:167], v147, off
	v_lshlrev_b32_e32 v148, 16, v148
	v_mul_f32_e32 v148, v40, v148
	v_cvt_pk_bf16_f32 v148, v148, s0
	global_store_short v[168:169], v148, off
	v_lshlrev_b32_e32 v149, 16, v149
	v_mul_f32_e32 v149, v41, v149
	v_cvt_pk_bf16_f32 v149, v149, s0
	global_store_short v[170:171], v149, off
	v_lshlrev_b32_e32 v150, 16, v150
	v_mul_f32_e32 v150, v42, v150
	v_cvt_pk_bf16_f32 v150, v150, s0
	global_store_short v[172:173], v150, off
	v_lshlrev_b32_e32 v151, 16, v151
	v_mul_f32_e32 v151, v43, v151
	v_cvt_pk_bf16_f32 v151, v151, s0
	global_store_short v[174:175], v151, off
	v_lshlrev_b32_e32 v152, 16, v152
	v_mul_f32_e32 v152, v36, v152
	v_cvt_pk_bf16_f32 v152, v152, s0
	global_store_short v[176:177], v152, off
	v_lshlrev_b32_e32 v153, 16, v153
	v_mul_f32_e32 v153, v37, v153
	v_cvt_pk_bf16_f32 v153, v153, s0
	global_store_short v[178:179], v153, off
	v_lshlrev_b32_e32 v154, 16, v154
	v_mul_f32_e32 v154, v38, v154
	v_cvt_pk_bf16_f32 v154, v154, s0
	global_store_short v[198:199], v154, off
	v_lshlrev_b32_e32 v155, 16, v155
	v_mul_f32_e32 v155, v39, v155
	v_cvt_pk_bf16_f32 v155, v155, s0
	global_store_short v[200:201], v155, off
	v_lshlrev_b32_e32 v156, 16, v156
	v_mul_f32_e32 v156, v32, v156
	v_cvt_pk_bf16_f32 v156, v156, s0
	global_store_short v[202:203], v156, off
	v_lshlrev_b32_e32 v157, 16, v157
	v_mul_f32_e32 v157, v33, v157
	v_cvt_pk_bf16_f32 v157, v157, s0
	global_store_short v[204:205], v157, off
	v_lshlrev_b32_e32 v158, 16, v158
	v_mul_f32_e32 v158, v34, v158
	v_cvt_pk_bf16_f32 v158, v158, s0
	global_store_short v[206:207], v158, off
	v_lshlrev_b32_e32 v159, 16, v159
	v_mul_f32_e32 v159, v35, v159
	v_cvt_pk_bf16_f32 v159, v159, s0
	global_store_short v[208:209], v159, off
	s_cbranch_execnz .LBB0_584
